# dense: one static s_setprio 1 for waves 4-7 around the main loop (strategy 7.4)
# baseline (speedup 1.0000x reference)
; #define PP_BAR(VM) do { if (VM) { asm volatile("s_waitcnt vmcnt(4) lgkmcnt(0)\n\ts_barrier" ::: "memory"); } else { asm volatile("s_waitcnt vmcnt(0) lgkmcnt(0)\n\ts_barrier" ::: "memory"); } } while (0)
; #define PP_BAR_PLAIN() asm volatile("s_waitcnt lgkmcnt(0)\n\ts_barrier" ::: "memory")
;     ...
;   } else if constexpr (MK_PP) {
;     const bool grpB = wid >= 4;
;     ...
;     m_reg = 0.f; f32x16 negm = f32x16{};
;     ...
;     if (grpB) PP_BAR_PLAIN();
;     qkt(pA0, pA1, KBUF(0), qr, r32, hi);
;     if (grpB) PP_BAR(2 < NT); else PP_BAR_PLAIN();
;     for (int t = 0; t < NT; ++t) {
.LBB0_55:
	s_and_b64 vcc, exec, s[82:83]
	s_cbranch_vccz .Lsprio_skip
	s_setprio 1

; __device__ __forceinline__ void partialSM_neg(f32x16& p0, f32x16& p1, float& m_reg, f32x16& negm, float& alpha, int bounded) {
;   if (bounded) {
;     alpha = 1.f;
; #pragma unroll
;     for (int r = 0; r < 16; ++r) p0[r] = __builtin_amdgcn_exp2f(p0[r]);
;     return;
;   }
;   float pmax = p0[0];
; #pragma unroll
;   for (int r = 1; r < 16; ++r) pmax = fmaxf(pmax, p0[r]);
; #pragma unroll
;   for (int r = 0; r < 16; ++r) pmax = fmaxf(pmax, p1[r]);
;   { auto rr = __builtin_amdgcn_permlane32_swap(__float_as_uint(pmax), __float_as_uint(pmax), false, false);
;     pmax = fmaxf(__uint_as_float(rr[0]), __uint_as_float(rr[1])); }
;   if (__builtin_expect(__all(pmax <= THR), 1)) { alpha = 1.f; }
.LBB0_76:
	s_setprio 0
	s_and_b64 vcc, exec, s[40:41]
	v_mov_b32_e32 v191, 1.0
	s_cbranch_vccnz .LBB0_78
	v_max_f32_e32 v114, v99, v99
	v_max_f32_e32 v115, v98, v98
	v_max_f32_e32 v114, v115, v114
	v_max3_f32 v114, v114, v100, v101
	v_max3_f32 v114, v114, v102, v103
	v_max3_f32 v114, v114, v104, v105
	v_max3_f32 v114, v114, v106, v107
	v_max3_f32 v114, v114, v108, v109
	v_max3_f32 v114, v114, v110, v111
	v_max3_f32 v114, v114, v112, v113
	v_max3_f32 v114, v114, v82, v83
	v_max3_f32 v114, v114, v84, v85
	v_max3_f32 v114, v114, v86, v87
	v_max3_f32 v114, v114, v88, v89
	v_max3_f32 v114, v114, v90, v91
	v_max3_f32 v114, v114, v92, v93
	v_max3_f32 v114, v114, v94, v95
	v_max3_f32 v114, v114, v96, v97
	v_mov_b32_e32 v115, v114
	s_nop 1
	v_permlane32_swap_b32_e32 v114, v115
	v_max_f32_e32 v115, v115, v115
	v_max_f32_e32 v114, v114, v114
	v_max_f32_e32 v114, v114, v115
	v_cmp_ge_f32_e32 vcc, s91, v114
	s_cmp_eq_u64 vcc, exec
	v_mov_b32_e32 v191, 1.0
	s_cbranch_scc0 .LBB0_121
